# combined GEMM entry trims on top: batched rstd-table loads, closed-form next-unit decode, SGPR-base addressing for the first-super-phase stage loads
# speedup vs baseline: 1.0037x; 1.0037x over previous
.LBB0_487:
	s_add_u32 s36, s36, 0x80
	s_addc_u32 s37, s37, 0
	s_add_u32 s38, s58, 0x100
	s_addc_u32 s39, s59, 0
	s_mov_b32 s46, 0
	s_add_i32 s58, s46, 2
	s_add_u32 s59, s36, 0x80
	s_addc_u32 s47, s37, 0
	s_add_i32 s96, 0, 0x10000
	s_cmp_eq_u32 s72, s46
	s_cselect_b32 s47, s55, s47
	s_cselect_b32 s46, s54, s59
	v_add_u32_e32 v146, s96, v149
	s_cselect_b32 vcc_hi, s57, s39
	s_cselect_b32 vcc_lo, s56, s38
	s_add_i32 s59, 0, 0x14000
	s_waitcnt lgkmcnt(0)
	ds_read_b128 v[142:145], v146
	ds_read_b128 v[158:161], v146 offset:1024
	ds_read_b128 v[166:169], v146 offset:2048
	ds_read_b128 v[170:173], v146 offset:3072
	v_add_u32_e32 v146, s59, v149
	ds_read_b128 v[174:177], v146
	ds_read_b128 v[178:181], v146 offset:1024
	ds_read_b128 v[182:185], v146 offset:2048
	ds_read_b128 v[186:189], v146 offset:3072
	s_add_i32 m0, s61, 0xc000
	ds_read_b128 v[190:193], v157
	ds_read_b128 v[194:197], v157 offset:1024
	ds_read_b128 v[198:201], v157 offset:2048
	ds_read_b128 v[202:205], v157 offset:3072
	ds_read_b128 v[230:233], v157 offset:4096
	ds_read_b128 v[234:237], v157 offset:5120
	ds_read_b128 v[238:241], v157 offset:6144
	ds_read_b128 v[242:245], v157 offset:7168
	global_load_lds_dwordx4 v138, s[36:37]
	s_add_i32 m0, s61, 0xe000
	s_nop 0
	global_load_lds_dwordx4 v140, s[36:37]
	s_waitcnt vmcnt(8)
	s_waitcnt lgkmcnt(0)
	s_barrier
	s_setprio 1
	s_waitcnt lgkmcnt(0)
	v_mfma_f32_16x16x32_bf16 v[124:127], v[142:145], v[190:193], 0
	v_mfma_f32_16x16x32_bf16 v[120:123], v[166:169], v[190:193], 0
	v_mfma_f32_16x16x32_bf16 v[108:111], v[142:145], v[198:201], 0
	v_mfma_f32_16x16x32_bf16 v[104:107], v[166:169], v[198:201], 0
	v_mfma_f32_16x16x32_bf16 v[92:95], v[142:145], v[230:233], 0
	v_mfma_f32_16x16x32_bf16 v[88:91], v[166:169], v[230:233], 0
	v_mfma_f32_16x16x32_bf16 v[76:79], v[142:145], v[238:241], 0
	v_mfma_f32_16x16x32_bf16 v[72:75], v[166:169], v[238:241], 0
	v_mfma_f32_16x16x32_bf16 v[124:127], v[158:161], v[194:197], v[124:127]
	v_mfma_f32_16x16x32_bf16 v[120:123], v[170:173], v[194:197], v[120:123]
	v_mfma_f32_16x16x32_bf16 v[108:111], v[158:161], v[202:205], v[108:111]
	v_mfma_f32_16x16x32_bf16 v[104:107], v[170:173], v[202:205], v[104:107]
	v_mfma_f32_16x16x32_bf16 v[92:95], v[158:161], v[234:237], v[92:95]
	v_mfma_f32_16x16x32_bf16 v[88:91], v[170:173], v[234:237], v[88:91]
	v_mfma_f32_16x16x32_bf16 v[76:79], v[158:161], v[242:245], v[76:79]
	v_mfma_f32_16x16x32_bf16 v[72:75], v[170:173], v[242:245], v[72:75]
	s_setprio 0
	s_setprio 1
	v_mfma_f32_16x16x32_bf16 v[116:119], v[174:177], v[190:193], 0
	v_mfma_f32_16x16x32_bf16 v[112:115], v[182:185], v[190:193], 0
	v_mfma_f32_16x16x32_bf16 v[100:103], v[174:177], v[198:201], 0
	v_mfma_f32_16x16x32_bf16 v[96:99], v[182:185], v[198:201], 0
	v_mfma_f32_16x16x32_bf16 v[84:87], v[174:177], v[230:233], 0
	v_mfma_f32_16x16x32_bf16 v[80:83], v[182:185], v[230:233], 0
	v_mfma_f32_16x16x32_bf16 v[68:71], v[174:177], v[238:241], 0
	v_mfma_f32_16x16x32_bf16 v[64:67], v[182:185], v[238:241], 0
	v_mfma_f32_16x16x32_bf16 v[116:119], v[178:181], v[194:197], v[116:119]
	v_mfma_f32_16x16x32_bf16 v[112:115], v[186:189], v[194:197], v[112:115]
	v_mfma_f32_16x16x32_bf16 v[100:103], v[178:181], v[202:205], v[100:103]
	v_mfma_f32_16x16x32_bf16 v[96:99], v[186:189], v[202:205], v[96:99]
	v_mfma_f32_16x16x32_bf16 v[84:87], v[178:181], v[234:237], v[84:87]
	v_mfma_f32_16x16x32_bf16 v[80:83], v[186:189], v[234:237], v[80:83]
	v_mfma_f32_16x16x32_bf16 v[68:71], v[178:181], v[242:245], v[68:71]
	v_mfma_f32_16x16x32_bf16 v[64:67], v[186:189], v[242:245], v[64:67]
	s_setprio 0
	s_barrier
	s_add_i32 s96, s96, s60
	v_lshl_add_u64 v[146:147], vcc, 0, v[130:131]
	s_mov_b32 m0, s96
	ds_read_b128 v[190:193], v157 offset:16384
	ds_read_b128 v[194:197], v157 offset:17408
	ds_read_b128 v[198:201], v157 offset:18432
	ds_read_b128 v[202:205], v157 offset:19456
	ds_read_b128 v[230:233], v157 offset:20480
	ds_read_b128 v[234:237], v157 offset:21504
	ds_read_b128 v[238:241], v157 offset:22528
	ds_read_b128 v[242:245], v157 offset:23552
	global_load_lds_dwordx4 v[146:147], off
	s_add_i32 m0, s96, 0x2000
	v_lshl_add_u64 v[206:207], vcc, 0, v[134:135]
	s_add_u32 vcc_lo, vcc_lo, s26
	s_addc_u32 vcc_hi, vcc_hi, 0
	s_add_i32 s59, s59, s60
	global_load_lds_dwordx4 v[206:207], off
	v_lshl_add_u64 v[246:247], vcc, 0, v[130:131]
	s_mov_b32 m0, s59
	v_lshl_add_u64 v[248:249], vcc, 0, v[134:135]
	global_load_lds_dwordx4 v[246:247], off
	s_add_i32 m0, s59, 0x2000
	v_lshl_add_u64 v[250:251], s[46:47], 0, v[128:129]
	global_load_lds_dwordx4 v[248:249], off
	s_mov_b32 m0, s61
	v_lshl_add_u64 v[252:253], s[46:47], 0, v[132:133]
	global_load_lds_dwordx4 v[250:251], off
	s_mov_b32 m0, s62
	s_nop 0
	global_load_lds_dwordx4 v[252:253], off
	s_waitcnt vmcnt(8)
	s_waitcnt lgkmcnt(0)
	s_barrier
	s_setprio 1
	s_waitcnt lgkmcnt(0)
	v_mfma_f32_16x16x32_bf16 v[60:63], v[142:145], v[190:193], 0
	v_mfma_f32_16x16x32_bf16 v[56:59], v[166:169], v[190:193], 0
	v_mfma_f32_16x16x32_bf16 v[44:47], v[142:145], v[198:201], 0
	v_mfma_f32_16x16x32_bf16 v[40:43], v[166:169], v[198:201], 0
	v_mfma_f32_16x16x32_bf16 v[28:31], v[142:145], v[230:233], 0
	v_mfma_f32_16x16x32_bf16 v[24:27], v[166:169], v[230:233], 0
	v_mfma_f32_16x16x32_bf16 v[12:15], v[142:145], v[238:241], 0
	v_mfma_f32_16x16x32_bf16 v[8:11], v[166:169], v[238:241], 0
	v_mfma_f32_16x16x32_bf16 v[60:63], v[158:161], v[194:197], v[60:63]
	v_mfma_f32_16x16x32_bf16 v[56:59], v[170:173], v[194:197], v[56:59]
	v_mfma_f32_16x16x32_bf16 v[44:47], v[158:161], v[202:205], v[44:47]
	v_mfma_f32_16x16x32_bf16 v[40:43], v[170:173], v[202:205], v[40:43]
	v_mfma_f32_16x16x32_bf16 v[28:31], v[158:161], v[234:237], v[28:31]
	v_mfma_f32_16x16x32_bf16 v[24:27], v[170:173], v[234:237], v[24:27]
	v_mfma_f32_16x16x32_bf16 v[12:15], v[158:161], v[242:245], v[12:15]
	v_mfma_f32_16x16x32_bf16 v[8:11], v[170:173], v[242:245], v[8:11]
	s_setprio 0
	s_setprio 1
	v_mfma_f32_16x16x32_bf16 v[52:55], v[174:177], v[190:193], 0
	v_mfma_f32_16x16x32_bf16 v[48:51], v[182:185], v[190:193], 0
	v_mfma_f32_16x16x32_bf16 v[36:39], v[174:177], v[198:201], 0
	v_mfma_f32_16x16x32_bf16 v[32:35], v[182:185], v[198:201], 0
	v_mfma_f32_16x16x32_bf16 v[20:23], v[174:177], v[230:233], 0
	v_mfma_f32_16x16x32_bf16 v[16:19], v[182:185], v[230:233], 0
	v_mfma_f32_16x16x32_bf16 v[4:7], v[174:177], v[238:241], 0
	v_mfma_f32_16x16x32_bf16 v[0:3], v[182:185], v[238:241], 0
	v_mfma_f32_16x16x32_bf16 v[52:55], v[178:181], v[194:197], v[52:55]
	v_mfma_f32_16x16x32_bf16 v[48:51], v[186:189], v[194:197], v[48:51]
	v_mfma_f32_16x16x32_bf16 v[36:39], v[178:181], v[202:205], v[36:39]
	v_mfma_f32_16x16x32_bf16 v[32:35], v[186:189], v[202:205], v[32:35]
	v_mfma_f32_16x16x32_bf16 v[20:23], v[178:181], v[234:237], v[20:23]
	v_mfma_f32_16x16x32_bf16 v[16:19], v[186:189], v[234:237], v[16:19]
	v_mfma_f32_16x16x32_bf16 v[4:7], v[178:181], v[242:245], v[4:7]
	v_mfma_f32_16x16x32_bf16 v[0:3], v[186:189], v[242:245], v[0:3]
	s_setprio 0
	s_barrier
	s_add_i32 s59, 0, 0x18000
	v_add_u32_e32 v162, s59, v149
	s_add_i32 s96, 0, 0x1c000
	ds_read_b128 v[142:145], v162
	ds_read_b128 v[158:161], v162 offset:1024
	ds_read_b128 v[166:169], v162 offset:2048
	ds_read_b128 v[170:173], v162 offset:3072
	v_add_u32_e32 v162, s96, v149
	ds_read_b128 v[174:177], v162
	ds_read_b128 v[178:181], v162 offset:1024
	ds_read_b128 v[182:185], v162 offset:2048
	ds_read_b128 v[186:189], v162 offset:3072
	s_add_u32 s46, s46, s26
	s_addc_u32 s47, s47, 0
	s_mov_b32 m0, s63
	ds_read_b128 v[190:193], v157 offset:32768
	ds_read_b128 v[194:197], v157 offset:33792
	ds_read_b128 v[198:201], v157 offset:34816
	ds_read_b128 v[202:205], v157 offset:35840
	ds_read_b128 v[230:233], v157 offset:36864
	ds_read_b128 v[234:237], v157 offset:37888
	ds_read_b128 v[238:241], v157 offset:38912
	ds_read_b128 v[242:245], v157 offset:39936
	global_load_lds_dwordx4 v128, s[46:47]
	s_mov_b32 m0, s64
	s_nop 0
	global_load_lds_dwordx4 v132, s[46:47]
	s_waitcnt vmcnt(8)
	s_waitcnt lgkmcnt(0)
	s_barrier
	s_setprio 1
	s_waitcnt lgkmcnt(0)
	v_mfma_f32_16x16x32_bf16 v[124:127], v[142:145], v[190:193], v[124:127]
	v_mfma_f32_16x16x32_bf16 v[120:123], v[166:169], v[190:193], v[120:123]
	v_mfma_f32_16x16x32_bf16 v[108:111], v[142:145], v[198:201], v[108:111]
	v_mfma_f32_16x16x32_bf16 v[104:107], v[166:169], v[198:201], v[104:107]
	v_mfma_f32_16x16x32_bf16 v[92:95], v[142:145], v[230:233], v[92:95]
	v_mfma_f32_16x16x32_bf16 v[88:91], v[166:169], v[230:233], v[88:91]
	v_mfma_f32_16x16x32_bf16 v[76:79], v[142:145], v[238:241], v[76:79]
	v_mfma_f32_16x16x32_bf16 v[72:75], v[166:169], v[238:241], v[72:75]
	v_mfma_f32_16x16x32_bf16 v[124:127], v[158:161], v[194:197], v[124:127]
	v_mfma_f32_16x16x32_bf16 v[120:123], v[170:173], v[194:197], v[120:123]
	v_mfma_f32_16x16x32_bf16 v[108:111], v[158:161], v[202:205], v[108:111]
	v_mfma_f32_16x16x32_bf16 v[104:107], v[170:173], v[202:205], v[104:107]
	v_mfma_f32_16x16x32_bf16 v[92:95], v[158:161], v[234:237], v[92:95]
	v_mfma_f32_16x16x32_bf16 v[88:91], v[170:173], v[234:237], v[88:91]
	v_mfma_f32_16x16x32_bf16 v[76:79], v[158:161], v[242:245], v[76:79]
	v_mfma_f32_16x16x32_bf16 v[72:75], v[170:173], v[242:245], v[72:75]
	s_setprio 0
	s_setprio 1
	v_mfma_f32_16x16x32_bf16 v[116:119], v[174:177], v[190:193], v[116:119]
	v_mfma_f32_16x16x32_bf16 v[112:115], v[182:185], v[190:193], v[112:115]
	v_mfma_f32_16x16x32_bf16 v[100:103], v[174:177], v[198:201], v[100:103]
	v_mfma_f32_16x16x32_bf16 v[96:99], v[182:185], v[198:201], v[96:99]
	v_mfma_f32_16x16x32_bf16 v[84:87], v[174:177], v[230:233], v[84:87]
	v_mfma_f32_16x16x32_bf16 v[80:83], v[182:185], v[230:233], v[80:83]
	v_mfma_f32_16x16x32_bf16 v[68:71], v[174:177], v[238:241], v[68:71]
	v_mfma_f32_16x16x32_bf16 v[64:67], v[182:185], v[238:241], v[64:67]
	v_mfma_f32_16x16x32_bf16 v[116:119], v[178:181], v[194:197], v[116:119]
	v_mfma_f32_16x16x32_bf16 v[112:115], v[186:189], v[194:197], v[112:115]
	v_mfma_f32_16x16x32_bf16 v[100:103], v[178:181], v[202:205], v[100:103]
	v_mfma_f32_16x16x32_bf16 v[96:99], v[186:189], v[202:205], v[96:99]
	v_mfma_f32_16x16x32_bf16 v[84:87], v[178:181], v[234:237], v[84:87]
	v_mfma_f32_16x16x32_bf16 v[80:83], v[186:189], v[234:237], v[80:83]
	v_mfma_f32_16x16x32_bf16 v[68:71], v[178:181], v[242:245], v[68:71]
	v_mfma_f32_16x16x32_bf16 v[64:67], v[186:189], v[242:245], v[64:67]
	s_setprio 0
	s_barrier
	s_add_i32 s46, s59, s60
	v_lshl_add_u64 v[146:147], v[146:147], 0, s[8:9]
	s_mov_b32 m0, s46
	ds_read_b128 v[190:193], v157 offset:49152
	ds_read_b128 v[194:197], v157 offset:50176
	ds_read_b128 v[198:201], v157 offset:51200
	ds_read_b128 v[202:205], v157 offset:52224
	ds_read_b128 v[230:233], v157 offset:53248
	ds_read_b128 v[234:237], v157 offset:54272
	ds_read_b128 v[238:241], v157 offset:55296
	ds_read_b128 v[242:245], v157 offset:56320
	global_load_lds_dwordx4 v[146:147], off
	v_lshl_add_u64 v[146:147], v[206:207], 0, s[8:9]
	s_add_i32 m0, s46, 0x2000
	s_add_i32 s46, s96, s60
	global_load_lds_dwordx4 v[146:147], off
	v_lshl_add_u64 v[146:147], v[246:247], 0, s[8:9]
	s_mov_b32 m0, s46
	s_nop 0
	global_load_lds_dwordx4 v[146:147], off
	v_lshl_add_u64 v[146:147], v[248:249], 0, s[8:9]
	s_add_i32 m0, s46, 0x2000
	s_nop 0
	global_load_lds_dwordx4 v[146:147], off
	v_lshl_add_u64 v[146:147], v[250:251], 0, s[8:9]
	s_mov_b32 m0, s70
	s_nop 0
	global_load_lds_dwordx4 v[146:147], off
	v_lshl_add_u64 v[146:147], v[252:253], 0, s[8:9]
	s_mov_b32 m0, s71
	s_nop 0
	global_load_lds_dwordx4 v[146:147], off
	s_waitcnt vmcnt(8)
	s_waitcnt lgkmcnt(0)
	s_barrier
	s_setprio 1
	s_waitcnt lgkmcnt(0)
	v_mfma_f32_16x16x32_bf16 v[60:63], v[142:145], v[190:193], v[60:63]
	v_mfma_f32_16x16x32_bf16 v[56:59], v[166:169], v[190:193], v[56:59]
	v_mfma_f32_16x16x32_bf16 v[44:47], v[142:145], v[198:201], v[44:47]
	v_mfma_f32_16x16x32_bf16 v[40:43], v[166:169], v[198:201], v[40:43]
	v_mfma_f32_16x16x32_bf16 v[28:31], v[142:145], v[230:233], v[28:31]
	v_mfma_f32_16x16x32_bf16 v[24:27], v[166:169], v[230:233], v[24:27]
	v_mfma_f32_16x16x32_bf16 v[12:15], v[142:145], v[238:241], v[12:15]
	v_mfma_f32_16x16x32_bf16 v[8:11], v[166:169], v[238:241], v[8:11]
	v_mfma_f32_16x16x32_bf16 v[60:63], v[158:161], v[194:197], v[60:63]
	v_mfma_f32_16x16x32_bf16 v[56:59], v[170:173], v[194:197], v[56:59]
	v_mfma_f32_16x16x32_bf16 v[44:47], v[158:161], v[202:205], v[44:47]
	v_mfma_f32_16x16x32_bf16 v[40:43], v[170:173], v[202:205], v[40:43]
	v_mfma_f32_16x16x32_bf16 v[28:31], v[158:161], v[234:237], v[28:31]
	v_mfma_f32_16x16x32_bf16 v[24:27], v[170:173], v[234:237], v[24:27]
	v_mfma_f32_16x16x32_bf16 v[12:15], v[158:161], v[242:245], v[12:15]
	v_mfma_f32_16x16x32_bf16 v[8:11], v[170:173], v[242:245], v[8:11]
	s_setprio 0
	s_setprio 1
	v_mfma_f32_16x16x32_bf16 v[52:55], v[174:177], v[190:193], v[52:55]
	v_mfma_f32_16x16x32_bf16 v[48:51], v[182:185], v[190:193], v[48:51]
	v_mfma_f32_16x16x32_bf16 v[36:39], v[174:177], v[198:201], v[36:39]
	v_mfma_f32_16x16x32_bf16 v[32:35], v[182:185], v[198:201], v[32:35]
	v_mfma_f32_16x16x32_bf16 v[20:23], v[174:177], v[230:233], v[20:23]
	v_mfma_f32_16x16x32_bf16 v[16:19], v[182:185], v[230:233], v[16:19]
	v_mfma_f32_16x16x32_bf16 v[4:7], v[174:177], v[238:241], v[4:7]
	v_mfma_f32_16x16x32_bf16 v[0:3], v[182:185], v[238:241], v[0:3]
	v_mfma_f32_16x16x32_bf16 v[52:55], v[178:181], v[194:197], v[52:55]
	v_mfma_f32_16x16x32_bf16 v[48:51], v[186:189], v[194:197], v[48:51]
	v_mfma_f32_16x16x32_bf16 v[36:39], v[178:181], v[202:205], v[36:39]
	v_mfma_f32_16x16x32_bf16 v[32:35], v[186:189], v[202:205], v[32:35]
	v_mfma_f32_16x16x32_bf16 v[20:23], v[178:181], v[234:237], v[20:23]
	v_mfma_f32_16x16x32_bf16 v[16:19], v[186:189], v[234:237], v[16:19]
	v_mfma_f32_16x16x32_bf16 v[4:7], v[178:181], v[242:245], v[4:7]
	v_mfma_f32_16x16x32_bf16 v[0:3], v[186:189], v[242:245], v[0:3]
	s_setprio 0
	s_barrier
	s_add_u32 s36, s36, 0x100
	s_addc_u32 s37, s37, 0
	s_add_u32 s38, s38, 0x100
	s_addc_u32 s39, s39, 0
	s_cmp_ge_u32 s58, s66
	s_mov_b32 s46, s58
.LBB0_488:
	s_add_i32 s58, s46, 2
	s_add_u32 s59, s36, 0x80
	s_addc_u32 s47, s37, 0
	s_add_i32 s96, 0, 0x10000
	s_cmp_eq_u32 s72, s46
	s_cselect_b32 s47, s55, s47
	s_cselect_b32 s46, s54, s59
	v_add_u32_e32 v146, s96, v149
	s_cselect_b32 vcc_hi, s57, s39
	s_cselect_b32 vcc_lo, s56, s38
	s_add_i32 s59, 0, 0x14000
	s_waitcnt lgkmcnt(0)
	ds_read_b128 v[142:145], v146
	ds_read_b128 v[158:161], v146 offset:1024
	ds_read_b128 v[166:169], v146 offset:2048
	ds_read_b128 v[170:173], v146 offset:3072
	v_add_u32_e32 v146, s59, v149
	ds_read_b128 v[174:177], v146
	ds_read_b128 v[178:181], v146 offset:1024
	ds_read_b128 v[182:185], v146 offset:2048
	ds_read_b128 v[186:189], v146 offset:3072
	s_add_i32 m0, s61, 0xc000
	ds_read_b128 v[190:193], v157
	ds_read_b128 v[194:197], v157 offset:1024
	ds_read_b128 v[198:201], v157 offset:2048
	ds_read_b128 v[202:205], v157 offset:3072
	ds_read_b128 v[230:233], v157 offset:4096
	ds_read_b128 v[234:237], v157 offset:5120
	ds_read_b128 v[238:241], v157 offset:6144
	ds_read_b128 v[242:245], v157 offset:7168
	global_load_lds_dwordx4 v138, s[36:37]
	s_add_i32 m0, s61, 0xe000
	s_nop 0
	global_load_lds_dwordx4 v140, s[36:37]
	s_waitcnt vmcnt(8)
	s_waitcnt lgkmcnt(0)
	s_barrier
	s_setprio 1
	s_waitcnt lgkmcnt(0)
	v_mfma_f32_16x16x32_bf16 v[124:127], v[142:145], v[190:193], v[124:127]
	v_mfma_f32_16x16x32_bf16 v[120:123], v[166:169], v[190:193], v[120:123]
	v_mfma_f32_16x16x32_bf16 v[108:111], v[142:145], v[198:201], v[108:111]
	v_mfma_f32_16x16x32_bf16 v[104:107], v[166:169], v[198:201], v[104:107]
	v_mfma_f32_16x16x32_bf16 v[92:95], v[142:145], v[230:233], v[92:95]
	v_mfma_f32_16x16x32_bf16 v[88:91], v[166:169], v[230:233], v[88:91]
	v_mfma_f32_16x16x32_bf16 v[76:79], v[142:145], v[238:241], v[76:79]
	v_mfma_f32_16x16x32_bf16 v[72:75], v[166:169], v[238:241], v[72:75]
	v_mfma_f32_16x16x32_bf16 v[124:127], v[158:161], v[194:197], v[124:127]
	v_mfma_f32_16x16x32_bf16 v[120:123], v[170:173], v[194:197], v[120:123]
	v_mfma_f32_16x16x32_bf16 v[108:111], v[158:161], v[202:205], v[108:111]
	v_mfma_f32_16x16x32_bf16 v[104:107], v[170:173], v[202:205], v[104:107]
	v_mfma_f32_16x16x32_bf16 v[92:95], v[158:161], v[234:237], v[92:95]
	v_mfma_f32_16x16x32_bf16 v[88:91], v[170:173], v[234:237], v[88:91]
	v_mfma_f32_16x16x32_bf16 v[76:79], v[158:161], v[242:245], v[76:79]
	v_mfma_f32_16x16x32_bf16 v[72:75], v[170:173], v[242:245], v[72:75]
	s_setprio 0
	s_setprio 1
	v_mfma_f32_16x16x32_bf16 v[116:119], v[174:177], v[190:193], v[116:119]
	v_mfma_f32_16x16x32_bf16 v[112:115], v[182:185], v[190:193], v[112:115]
	v_mfma_f32_16x16x32_bf16 v[100:103], v[174:177], v[198:201], v[100:103]
	v_mfma_f32_16x16x32_bf16 v[96:99], v[182:185], v[198:201], v[96:99]
	v_mfma_f32_16x16x32_bf16 v[84:87], v[174:177], v[230:233], v[84:87]
	v_mfma_f32_16x16x32_bf16 v[80:83], v[182:185], v[230:233], v[80:83]
	v_mfma_f32_16x16x32_bf16 v[68:71], v[174:177], v[238:241], v[68:71]
	v_mfma_f32_16x16x32_bf16 v[64:67], v[182:185], v[238:241], v[64:67]
	v_mfma_f32_16x16x32_bf16 v[116:119], v[178:181], v[194:197], v[116:119]
	v_mfma_f32_16x16x32_bf16 v[112:115], v[186:189], v[194:197], v[112:115]
	v_mfma_f32_16x16x32_bf16 v[100:103], v[178:181], v[202:205], v[100:103]
	v_mfma_f32_16x16x32_bf16 v[96:99], v[186:189], v[202:205], v[96:99]
	v_mfma_f32_16x16x32_bf16 v[84:87], v[178:181], v[234:237], v[84:87]
	v_mfma_f32_16x16x32_bf16 v[80:83], v[186:189], v[234:237], v[80:83]
	v_mfma_f32_16x16x32_bf16 v[68:71], v[178:181], v[242:245], v[68:71]
	v_mfma_f32_16x16x32_bf16 v[64:67], v[186:189], v[242:245], v[64:67]
	s_setprio 0
	s_barrier
	s_add_i32 s96, s96, s60
	v_lshl_add_u64 v[146:147], vcc, 0, v[130:131]
	s_mov_b32 m0, s96
	ds_read_b128 v[190:193], v157 offset:16384
	ds_read_b128 v[194:197], v157 offset:17408
	ds_read_b128 v[198:201], v157 offset:18432
	ds_read_b128 v[202:205], v157 offset:19456
	ds_read_b128 v[230:233], v157 offset:20480
	ds_read_b128 v[234:237], v157 offset:21504
	ds_read_b128 v[238:241], v157 offset:22528
	ds_read_b128 v[242:245], v157 offset:23552
	global_load_lds_dwordx4 v[146:147], off
	s_add_i32 m0, s96, 0x2000
	v_lshl_add_u64 v[206:207], vcc, 0, v[134:135]
	s_add_u32 vcc_lo, vcc_lo, s26
	s_addc_u32 vcc_hi, vcc_hi, 0
	s_add_i32 s59, s59, s60
	global_load_lds_dwordx4 v[206:207], off
	v_lshl_add_u64 v[246:247], vcc, 0, v[130:131]
	s_mov_b32 m0, s59
	v_lshl_add_u64 v[248:249], vcc, 0, v[134:135]
	global_load_lds_dwordx4 v[246:247], off
	s_add_i32 m0, s59, 0x2000
	v_lshl_add_u64 v[250:251], s[46:47], 0, v[128:129]
	global_load_lds_dwordx4 v[248:249], off
	s_mov_b32 m0, s61
	v_lshl_add_u64 v[252:253], s[46:47], 0, v[132:133]
	global_load_lds_dwordx4 v[250:251], off
	s_mov_b32 m0, s62
	s_nop 0
	global_load_lds_dwordx4 v[252:253], off
	s_waitcnt vmcnt(8)
	s_waitcnt lgkmcnt(0)
	s_barrier
	s_setprio 1
	s_waitcnt lgkmcnt(0)
	v_mfma_f32_16x16x32_bf16 v[60:63], v[142:145], v[190:193], v[60:63]
	v_mfma_f32_16x16x32_bf16 v[56:59], v[166:169], v[190:193], v[56:59]
	v_mfma_f32_16x16x32_bf16 v[44:47], v[142:145], v[198:201], v[44:47]
	v_mfma_f32_16x16x32_bf16 v[40:43], v[166:169], v[198:201], v[40:43]
	v_mfma_f32_16x16x32_bf16 v[28:31], v[142:145], v[230:233], v[28:31]
	v_mfma_f32_16x16x32_bf16 v[24:27], v[166:169], v[230:233], v[24:27]
	v_mfma_f32_16x16x32_bf16 v[12:15], v[142:145], v[238:241], v[12:15]
	v_mfma_f32_16x16x32_bf16 v[8:11], v[166:169], v[238:241], v[8:11]
	v_mfma_f32_16x16x32_bf16 v[60:63], v[158:161], v[194:197], v[60:63]
	v_mfma_f32_16x16x32_bf16 v[56:59], v[170:173], v[194:197], v[56:59]
	v_mfma_f32_16x16x32_bf16 v[44:47], v[158:161], v[202:205], v[44:47]
	v_mfma_f32_16x16x32_bf16 v[40:43], v[170:173], v[202:205], v[40:43]
	v_mfma_f32_16x16x32_bf16 v[28:31], v[158:161], v[234:237], v[28:31]
	v_mfma_f32_16x16x32_bf16 v[24:27], v[170:173], v[234:237], v[24:27]
	v_mfma_f32_16x16x32_bf16 v[12:15], v[158:161], v[242:245], v[12:15]
	v_mfma_f32_16x16x32_bf16 v[8:11], v[170:173], v[242:245], v[8:11]
	s_setprio 0
	s_setprio 1
	v_mfma_f32_16x16x32_bf16 v[52:55], v[174:177], v[190:193], v[52:55]
	v_mfma_f32_16x16x32_bf16 v[48:51], v[182:185], v[190:193], v[48:51]
	v_mfma_f32_16x16x32_bf16 v[36:39], v[174:177], v[198:201], v[36:39]
	v_mfma_f32_16x16x32_bf16 v[32:35], v[182:185], v[198:201], v[32:35]
	v_mfma_f32_16x16x32_bf16 v[20:23], v[174:177], v[230:233], v[20:23]
	v_mfma_f32_16x16x32_bf16 v[16:19], v[182:185], v[230:233], v[16:19]
	v_mfma_f32_16x16x32_bf16 v[4:7], v[174:177], v[238:241], v[4:7]
	v_mfma_f32_16x16x32_bf16 v[0:3], v[182:185], v[238:241], v[0:3]
	v_mfma_f32_16x16x32_bf16 v[52:55], v[178:181], v[194:197], v[52:55]
	v_mfma_f32_16x16x32_bf16 v[48:51], v[186:189], v[194:197], v[48:51]
	v_mfma_f32_16x16x32_bf16 v[36:39], v[178:181], v[202:205], v[36:39]
	v_mfma_f32_16x16x32_bf16 v[32:35], v[186:189], v[202:205], v[32:35]
	v_mfma_f32_16x16x32_bf16 v[20:23], v[178:181], v[234:237], v[20:23]
	v_mfma_f32_16x16x32_bf16 v[16:19], v[186:189], v[234:237], v[16:19]
	v_mfma_f32_16x16x32_bf16 v[4:7], v[178:181], v[242:245], v[4:7]
	v_mfma_f32_16x16x32_bf16 v[0:3], v[186:189], v[242:245], v[0:3]
	s_setprio 0
	s_barrier
	s_add_i32 s59, 0, 0x18000
	v_add_u32_e32 v162, s59, v149
	s_add_i32 s96, 0, 0x1c000
	ds_read_b128 v[142:145], v162
	ds_read_b128 v[158:161], v162 offset:1024
	ds_read_b128 v[166:169], v162 offset:2048
	ds_read_b128 v[170:173], v162 offset:3072
	v_add_u32_e32 v162, s96, v149
	ds_read_b128 v[174:177], v162
	ds_read_b128 v[178:181], v162 offset:1024
	ds_read_b128 v[182:185], v162 offset:2048
	ds_read_b128 v[186:189], v162 offset:3072
	s_add_u32 s46, s46, s26
	s_addc_u32 s47, s47, 0
	s_mov_b32 m0, s63
	ds_read_b128 v[190:193], v157 offset:32768
	ds_read_b128 v[194:197], v157 offset:33792
	ds_read_b128 v[198:201], v157 offset:34816
	ds_read_b128 v[202:205], v157 offset:35840
	ds_read_b128 v[230:233], v157 offset:36864
	ds_read_b128 v[234:237], v157 offset:37888
	ds_read_b128 v[238:241], v157 offset:38912
	ds_read_b128 v[242:245], v157 offset:39936
	global_load_lds_dwordx4 v128, s[46:47]
	s_mov_b32 m0, s64
	s_nop 0
	global_load_lds_dwordx4 v132, s[46:47]
	s_waitcnt vmcnt(8)
	s_waitcnt lgkmcnt(0)
	s_barrier
	s_setprio 1
	s_waitcnt lgkmcnt(0)
	v_mfma_f32_16x16x32_bf16 v[124:127], v[142:145], v[190:193], v[124:127]
	v_mfma_f32_16x16x32_bf16 v[120:123], v[166:169], v[190:193], v[120:123]
	v_mfma_f32_16x16x32_bf16 v[108:111], v[142:145], v[198:201], v[108:111]
	v_mfma_f32_16x16x32_bf16 v[104:107], v[166:169], v[198:201], v[104:107]
	v_mfma_f32_16x16x32_bf16 v[92:95], v[142:145], v[230:233], v[92:95]
	v_mfma_f32_16x16x32_bf16 v[88:91], v[166:169], v[230:233], v[88:91]
	v_mfma_f32_16x16x32_bf16 v[76:79], v[142:145], v[238:241], v[76:79]
	v_mfma_f32_16x16x32_bf16 v[72:75], v[166:169], v[238:241], v[72:75]
	v_mfma_f32_16x16x32_bf16 v[124:127], v[158:161], v[194:197], v[124:127]
	v_mfma_f32_16x16x32_bf16 v[120:123], v[170:173], v[194:197], v[120:123]
	v_mfma_f32_16x16x32_bf16 v[108:111], v[158:161], v[202:205], v[108:111]
	v_mfma_f32_16x16x32_bf16 v[104:107], v[170:173], v[202:205], v[104:107]
	v_mfma_f32_16x16x32_bf16 v[92:95], v[158:161], v[234:237], v[92:95]
	v_mfma_f32_16x16x32_bf16 v[88:91], v[170:173], v[234:237], v[88:91]
	v_mfma_f32_16x16x32_bf16 v[76:79], v[158:161], v[242:245], v[76:79]
	v_mfma_f32_16x16x32_bf16 v[72:75], v[170:173], v[242:245], v[72:75]
	s_setprio 0
	s_setprio 1
	v_mfma_f32_16x16x32_bf16 v[116:119], v[174:177], v[190:193], v[116:119]
	v_mfma_f32_16x16x32_bf16 v[112:115], v[182:185], v[190:193], v[112:115]
	v_mfma_f32_16x16x32_bf16 v[100:103], v[174:177], v[198:201], v[100:103]
	v_mfma_f32_16x16x32_bf16 v[96:99], v[182:185], v[198:201], v[96:99]
	v_mfma_f32_16x16x32_bf16 v[84:87], v[174:177], v[230:233], v[84:87]
	v_mfma_f32_16x16x32_bf16 v[80:83], v[182:185], v[230:233], v[80:83]
	v_mfma_f32_16x16x32_bf16 v[68:71], v[174:177], v[238:241], v[68:71]
	v_mfma_f32_16x16x32_bf16 v[64:67], v[182:185], v[238:241], v[64:67]
	v_mfma_f32_16x16x32_bf16 v[116:119], v[178:181], v[194:197], v[116:119]
	v_mfma_f32_16x16x32_bf16 v[112:115], v[186:189], v[194:197], v[112:115]
	v_mfma_f32_16x16x32_bf16 v[100:103], v[178:181], v[202:205], v[100:103]
	v_mfma_f32_16x16x32_bf16 v[96:99], v[186:189], v[202:205], v[96:99]
	v_mfma_f32_16x16x32_bf16 v[84:87], v[178:181], v[234:237], v[84:87]
	v_mfma_f32_16x16x32_bf16 v[80:83], v[186:189], v[234:237], v[80:83]
	v_mfma_f32_16x16x32_bf16 v[68:71], v[178:181], v[242:245], v[68:71]
	v_mfma_f32_16x16x32_bf16 v[64:67], v[186:189], v[242:245], v[64:67]
	s_setprio 0
	s_barrier
	s_add_i32 s46, s59, s60
	v_lshl_add_u64 v[146:147], v[146:147], 0, s[8:9]
	s_mov_b32 m0, s46
	ds_read_b128 v[190:193], v157 offset:49152
	ds_read_b128 v[194:197], v157 offset:50176
	ds_read_b128 v[198:201], v157 offset:51200
	ds_read_b128 v[202:205], v157 offset:52224
	ds_read_b128 v[230:233], v157 offset:53248
	ds_read_b128 v[234:237], v157 offset:54272
	ds_read_b128 v[238:241], v157 offset:55296
	ds_read_b128 v[242:245], v157 offset:56320
	global_load_lds_dwordx4 v[146:147], off
	v_lshl_add_u64 v[146:147], v[206:207], 0, s[8:9]
	s_add_i32 m0, s46, 0x2000
	s_add_i32 s46, s96, s60
	global_load_lds_dwordx4 v[146:147], off
	v_lshl_add_u64 v[146:147], v[246:247], 0, s[8:9]
	s_mov_b32 m0, s46
	s_nop 0
	global_load_lds_dwordx4 v[146:147], off
	v_lshl_add_u64 v[146:147], v[248:249], 0, s[8:9]
	s_add_i32 m0, s46, 0x2000
	s_nop 0
	global_load_lds_dwordx4 v[146:147], off
	v_lshl_add_u64 v[146:147], v[250:251], 0, s[8:9]
	s_mov_b32 m0, s70
	s_nop 0
	global_load_lds_dwordx4 v[146:147], off
	v_lshl_add_u64 v[146:147], v[252:253], 0, s[8:9]
	s_mov_b32 m0, s71
	s_nop 0
	global_load_lds_dwordx4 v[146:147], off
	s_waitcnt vmcnt(8)
	s_waitcnt lgkmcnt(0)
	s_barrier
	s_setprio 1
	s_waitcnt lgkmcnt(0)
	v_mfma_f32_16x16x32_bf16 v[60:63], v[142:145], v[190:193], v[60:63]
	v_mfma_f32_16x16x32_bf16 v[56:59], v[166:169], v[190:193], v[56:59]
	v_mfma_f32_16x16x32_bf16 v[44:47], v[142:145], v[198:201], v[44:47]
	v_mfma_f32_16x16x32_bf16 v[40:43], v[166:169], v[198:201], v[40:43]
	v_mfma_f32_16x16x32_bf16 v[28:31], v[142:145], v[230:233], v[28:31]
	v_mfma_f32_16x16x32_bf16 v[24:27], v[166:169], v[230:233], v[24:27]
	v_mfma_f32_16x16x32_bf16 v[12:15], v[142:145], v[238:241], v[12:15]
	v_mfma_f32_16x16x32_bf16 v[8:11], v[166:169], v[238:241], v[8:11]
	v_mfma_f32_16x16x32_bf16 v[60:63], v[158:161], v[194:197], v[60:63]
	v_mfma_f32_16x16x32_bf16 v[56:59], v[170:173], v[194:197], v[56:59]
	v_mfma_f32_16x16x32_bf16 v[44:47], v[158:161], v[202:205], v[44:47]
	v_mfma_f32_16x16x32_bf16 v[40:43], v[170:173], v[202:205], v[40:43]
	v_mfma_f32_16x16x32_bf16 v[28:31], v[158:161], v[234:237], v[28:31]
	v_mfma_f32_16x16x32_bf16 v[24:27], v[170:173], v[234:237], v[24:27]
	v_mfma_f32_16x16x32_bf16 v[12:15], v[158:161], v[242:245], v[12:15]
	v_mfma_f32_16x16x32_bf16 v[8:11], v[170:173], v[242:245], v[8:11]
	s_setprio 0
	s_setprio 1
	v_mfma_f32_16x16x32_bf16 v[52:55], v[174:177], v[190:193], v[52:55]
	v_mfma_f32_16x16x32_bf16 v[48:51], v[182:185], v[190:193], v[48:51]
	v_mfma_f32_16x16x32_bf16 v[36:39], v[174:177], v[198:201], v[36:39]
	v_mfma_f32_16x16x32_bf16 v[32:35], v[182:185], v[198:201], v[32:35]
	v_mfma_f32_16x16x32_bf16 v[20:23], v[174:177], v[230:233], v[20:23]
	v_mfma_f32_16x16x32_bf16 v[16:19], v[182:185], v[230:233], v[16:19]
	v_mfma_f32_16x16x32_bf16 v[4:7], v[174:177], v[238:241], v[4:7]
	v_mfma_f32_16x16x32_bf16 v[0:3], v[182:185], v[238:241], v[0:3]
	v_mfma_f32_16x16x32_bf16 v[52:55], v[178:181], v[194:197], v[52:55]
	v_mfma_f32_16x16x32_bf16 v[48:51], v[186:189], v[194:197], v[48:51]
	v_mfma_f32_16x16x32_bf16 v[36:39], v[178:181], v[202:205], v[36:39]
	v_mfma_f32_16x16x32_bf16 v[32:35], v[186:189], v[202:205], v[32:35]
	v_mfma_f32_16x16x32_bf16 v[20:23], v[178:181], v[234:237], v[20:23]
	v_mfma_f32_16x16x32_bf16 v[16:19], v[186:189], v[234:237], v[16:19]
	v_mfma_f32_16x16x32_bf16 v[4:7], v[178:181], v[242:245], v[4:7]
	v_mfma_f32_16x16x32_bf16 v[0:3], v[186:189], v[242:245], v[0:3]
	s_setprio 0
	s_barrier
	s_add_u32 s36, s36, 0x100
	s_addc_u32 s37, s37, 0
	s_add_u32 s38, s38, 0x100
	s_addc_u32 s39, s39, 0
	s_cmp_ge_u32 s58, s66
	s_mov_b32 s46, s58
	s_cbranch_scc0 .LBB0_488
	s_and_b64 vcc, exec, s[52:53]
	s_cbranch_vccz .LBB0_492
	s_barrier
	s_cmp_lt_i32 s51, 1
	s_mov_b64 s[36:37], -1
	s_cbranch_scc0 .LBB0_493
